# XCD-local barriers: L1 invalidate issued by wave 1 right after the entry s_barrier, in parallel with wave 0's arrival/polling
# speedup vs baseline: 1.0128x; 1.0066x over previous
.LBB0_203:
	s_mov_b64 s[6:7], s[0:1]
	s_waitcnt vmcnt(0) lgkmcnt(0)
	v_mov_b64_e32 v[0:1], s[6:7]
	flat_load_dwordx2 v[0:1], v[0:1] offset:216
	s_getreg_b32 s3, hwreg(HW_REG_XCC_ID, 0, 4)
	s_waitcnt vmcnt(0)
	s_waitcnt lgkmcnt(0)
	s_barrier
	v_readlane_b32 s98, v254, 2
	v_readfirstlane_b32 s100, v176
	s_nop 0
	s_lshr_b32 s100, s100, 6
	s_cmp_eq_u32 s100, 1
	s_cselect_b32 s100, s98, 0
	s_cmp_lg_u32 s100, 0
	s_cbranch_scc0 .Lew_1
	buffer_inv sc1
	s_waitcnt vmcnt(0)
.Lew_1:
	s_and_saveexec_b64 s[48:49], s[24:25]
	s_cbranch_execz .LBB0_247
	s_add_i32 s6, 0, 0x23ff0
	v_mov_b32_e32 v2, s6
	s_waitcnt vmcnt(0) expcnt(0) lgkmcnt(0)
	ds_read_b32 v6, v2
	s_add_i32 s6, 0, 0x23ff4
	v_mov_b32_e32 v2, s6
	ds_read_b32 v4, v2
	s_and_b32 s3, s3, 15
	s_waitcnt lgkmcnt(1)
	v_cmp_ne_u32_e32 vcc, 0, v6
	s_cbranch_vccnz .LBB0_218
	v_readlane_b32 s6, v254, 0
	v_readlane_b32 s7, v254, 1
	s_load_dword s8, s[6:7], 0x14
	s_mov_b64 s[6:7], 0x1000
	v_lshl_add_u64 v[2:3], v[0:1], 0, s[6:7]
	s_mov_b64 s[6:7], 0x1100
	s_waitcnt lgkmcnt(0)
	v_lshl_add_u64 v[4:5], v[0:1], 0, s[6:7]
	s_lshr_b32 s10, s8, 16
	s_and_b32 s8, s8, 0xffff
	s_cmp_lg_u32 s8, 0
	s_cselect_b64 s[8:9], -1, 0
	s_cmp_lg_u64 s[8:9], 0
	s_addc_u32 s8, s79, 0
	s_cmp_lg_u32 s10, 0
	s_mul_i32 s26, s8, s68
	s_cselect_b64 s[8:9], -1, 0
	s_cmp_lg_u64 s[8:9], 0
	s_load_dword s8, s[0:1], 0xe8
	s_mov_b64 s[6:7], 0x1200
	v_lshl_add_u64 v[6:7], v[0:1], 0, s[6:7]
	s_mov_b64 s[6:7], 0x1300
	v_lshl_add_u64 v[8:9], v[0:1], 0, s[6:7]
	s_waitcnt lgkmcnt(0)
	s_addc_u32 s8, s8, 0
	s_mul_i32 s26, s26, s8
	s_mov_b32 s27, 1
	s_mov_b64 s[6:7], 0
	s_branch .LBB0_208

.LBB0_268:
	s_mov_b64 s[6:7], s[0:1]
	s_nop 0
	v_mov_b64_e32 v[0:1], s[6:7]
	flat_load_dwordx2 v[0:1], v[0:1] offset:216
	s_getreg_b32 s3, hwreg(HW_REG_XCC_ID, 0, 4)
	s_waitcnt vmcnt(0)
	s_waitcnt vmcnt(0) lgkmcnt(0)
	s_barrier
	v_readlane_b32 s98, v254, 2
	v_readfirstlane_b32 s100, v176
	s_nop 0
	s_lshr_b32 s100, s100, 6
	s_cmp_eq_u32 s100, 1
	s_cselect_b32 s100, s98, 0
	s_cmp_lg_u32 s100, 0
	s_cbranch_scc0 .Lew_2
	buffer_inv sc1
	s_waitcnt vmcnt(0)
.Lew_2:
	s_and_saveexec_b64 s[50:51], s[24:25]
	s_cbranch_execz .LBB0_312
	s_add_i32 s6, 0, 0x23ff0
	v_mov_b32_e32 v2, s6
	s_waitcnt vmcnt(0) expcnt(0) lgkmcnt(0)
	ds_read_b32 v6, v2
	s_add_i32 s6, 0, 0x23ff4
	v_mov_b32_e32 v2, s6
	ds_read_b32 v4, v2
	s_and_b32 s3, s3, 15
	s_waitcnt lgkmcnt(1)
	v_cmp_ne_u32_e32 vcc, 0, v6
	s_cbranch_vccnz .LBB0_283
	v_readlane_b32 s6, v254, 0
	v_readlane_b32 s7, v254, 1
	s_load_dword s8, s[6:7], 0x14
	s_mov_b64 s[6:7], 0x1000
	v_lshl_add_u64 v[2:3], v[0:1], 0, s[6:7]
	s_mov_b64 s[6:7], 0x1100
	s_waitcnt lgkmcnt(0)
	v_lshl_add_u64 v[4:5], v[0:1], 0, s[6:7]
	s_lshr_b32 s10, s8, 16
	s_and_b32 s8, s8, 0xffff
	s_cmp_lg_u32 s8, 0
	s_cselect_b64 s[8:9], -1, 0
	s_cmp_lg_u64 s[8:9], 0
	s_addc_u32 s8, s79, 0
	s_cmp_lg_u32 s10, 0
	s_mul_i32 s26, s8, s68
	s_cselect_b64 s[8:9], -1, 0
	s_cmp_lg_u64 s[8:9], 0
	s_load_dword s8, s[0:1], 0xe8
	s_mov_b64 s[6:7], 0x1200
	v_lshl_add_u64 v[6:7], v[0:1], 0, s[6:7]
	s_mov_b64 s[6:7], 0x1300
	v_lshl_add_u64 v[8:9], v[0:1], 0, s[6:7]
	s_waitcnt lgkmcnt(0)
	s_addc_u32 s8, s8, 0
	s_mul_i32 s26, s26, s8
	s_mov_b32 s27, 1
	s_mov_b64 s[6:7], 0
	s_branch .LBB0_273

.LBB0_334:
	v_writelane_b32 v255, s11, 0
	v_writelane_b32 v255, s12, 1
	v_writelane_b32 v255, s13, 2
	v_writelane_b32 v255, s14, 3
	v_writelane_b32 v255, s15, 4
	v_writelane_b32 v255, s16, 5
	v_writelane_b32 v255, s17, 6
	v_writelane_b32 v255, s20, 7
	v_writelane_b32 v255, s21, 8
	v_writelane_b32 v255, s22, 9
	v_writelane_b32 v255, s23, 10
	v_writelane_b32 v255, s28, 11
	v_writelane_b32 v255, s30, 12
	v_writelane_b32 v255, s34, 13
	v_writelane_b32 v255, s38, 14
	s_mov_b64 s[6:7], s[0:1]
	s_waitcnt lgkmcnt(0)
	s_barrier
	s_nop 0
	v_mov_b64_e32 v[0:1], s[6:7]
	flat_load_dwordx2 v[0:1], v[0:1] offset:216
	s_getreg_b32 s3, hwreg(HW_REG_XCC_ID, 0, 4)
	s_waitcnt vmcnt(0)
	s_waitcnt lgkmcnt(0)
	s_barrier
	v_readlane_b32 s98, v254, 2
	v_readfirstlane_b32 s100, v176
	s_nop 0
	s_lshr_b32 s100, s100, 6
	s_cmp_eq_u32 s100, 1
	s_cselect_b32 s100, s98, 0
	s_cmp_lg_u32 s100, 0
	s_cbranch_scc0 .Lb20_ew_3
	buffer_inv sc1
	s_waitcnt vmcnt(0)
.Lb20_ew_3:
	s_and_saveexec_b64 s[50:51], s[24:25]
	s_cbranch_execz .Lb20_BB0_411
	s_add_i32 s6, 0, 0x23ff0
	v_mov_b32_e32 v2, s6
	s_waitcnt vmcnt(0) expcnt(0) lgkmcnt(0)
	ds_read_b32 v6, v2
	s_add_i32 s6, 0, 0x23ff4
	v_mov_b32_e32 v2, s6
	ds_read_b32 v4, v2
	s_and_b32 s3, s3, 15
	s_waitcnt lgkmcnt(1)
	v_cmp_ne_u32_e32 vcc, 0, v6
	s_cbranch_vccnz .Lb20_BB0_382
	v_readlane_b32 s6, v254, 0
	v_readlane_b32 s7, v254, 1
	s_load_dword s8, s[6:7], 0x14
	s_mov_b64 s[6:7], 0x1000
	v_lshl_add_u64 v[2:3], v[0:1], 0, s[6:7]
	s_mov_b64 s[6:7], 0x1100
	s_waitcnt lgkmcnt(0)
	v_lshl_add_u64 v[4:5], v[0:1], 0, s[6:7]
	s_lshr_b32 s10, s8, 16
	s_and_b32 s8, s8, 0xffff
	s_cmp_lg_u32 s8, 0
	s_cselect_b64 s[8:9], -1, 0
	s_cmp_lg_u64 s[8:9], 0
	s_addc_u32 s8, s87, 0
	s_cmp_lg_u32 s10, 0
	s_mul_i32 s26, s8, s68
	s_cselect_b64 s[8:9], -1, 0
	s_cmp_lg_u64 s[8:9], 0
	s_load_dword s8, s[0:1], 0xe8
	s_mov_b64 s[6:7], 0x1200
	v_lshl_add_u64 v[6:7], v[0:1], 0, s[6:7]
	s_mov_b64 s[6:7], 0x1300
	v_lshl_add_u64 v[8:9], v[0:1], 0, s[6:7]
	s_waitcnt lgkmcnt(0)
	s_addc_u32 s8, s8, 0
	s_mul_i32 s26, s26, s8
	s_mov_b32 s27, 1
	s_mov_b64 s[6:7], 0
	s_branch .Lb20_BB0_372

.LBB0_367:
	s_mov_b64 s[6:7], s[0:1]
	s_waitcnt lgkmcnt(0)
	s_barrier
	s_nop 0
	v_mov_b64_e32 v[0:1], s[6:7]
	flat_load_dwordx2 v[0:1], v[0:1] offset:216
	s_getreg_b32 s3, hwreg(HW_REG_XCC_ID, 0, 4)
	s_waitcnt vmcnt(0)
	s_waitcnt lgkmcnt(0)
	s_barrier
	v_readlane_b32 s98, v254, 2
	v_readfirstlane_b32 s100, v176
	s_nop 0
	s_lshr_b32 s100, s100, 6
	s_cmp_eq_u32 s100, 1
	s_cselect_b32 s100, s98, 0
	s_cmp_lg_u32 s100, 0
	s_cbranch_scc0 .Lew_3
	buffer_inv sc1
	s_waitcnt vmcnt(0)

.LBB0_445:
	s_mov_b64 s[6:7], s[0:1]
	s_nop 0
	v_mov_b64_e32 v[0:1], s[6:7]
	flat_load_dwordx2 v[0:1], v[0:1] offset:216
	s_getreg_b32 s3, hwreg(HW_REG_XCC_ID, 0, 4)
	s_waitcnt vmcnt(0)
	s_waitcnt lgkmcnt(0)
	s_barrier
	v_readlane_b32 s98, v254, 2
	v_readfirstlane_b32 s100, v176
	s_nop 0
	s_lshr_b32 s100, s100, 6
	s_cmp_eq_u32 s100, 1
	s_cselect_b32 s100, s98, 0
	s_cmp_lg_u32 s100, 0
	s_cbranch_scc0 .Lew_4
	buffer_inv sc1
	s_waitcnt vmcnt(0)

.LBB0_629:
	s_mov_b64 s[8:9], s[0:1]
	s_nop 0
	v_mov_b64_e32 v[0:1], s[8:9]
	flat_load_dwordx2 v[0:1], v[0:1] offset:216
	s_getreg_b32 s3, hwreg(HW_REG_XCC_ID, 0, 4)
	s_waitcnt vmcnt(0)
	s_waitcnt vmcnt(0) lgkmcnt(0)
	s_barrier
	v_readlane_b32 s98, v254, 2
	v_readfirstlane_b32 s100, v176
	s_nop 0
	s_lshr_b32 s100, s100, 6
	s_cmp_eq_u32 s100, 1
	s_cselect_b32 s100, s98, 0
	s_cmp_lg_u32 s100, 0
	s_cbranch_scc0 .Lew_6
	buffer_inv sc1
	s_waitcnt vmcnt(0)
.Lew_6:
	s_and_saveexec_b64 s[50:51], s[24:25]
	s_cbranch_execz .LBB0_673
	s_add_i32 s8, 0, 0x23ff0
	v_mov_b32_e32 v2, s8
	s_waitcnt vmcnt(0) expcnt(0) lgkmcnt(0)
	ds_read_b32 v6, v2
	s_add_i32 s8, 0, 0x23ff4
	v_mov_b32_e32 v2, s8
	ds_read_b32 v4, v2
	s_and_b32 s3, s3, 15
	s_waitcnt lgkmcnt(1)
	v_cmp_ne_u32_e32 vcc, 0, v6
	s_cbranch_vccnz .LBB0_644
	v_readlane_b32 s8, v254, 0
	v_readlane_b32 s9, v254, 1
	s_load_dword s10, s[8:9], 0x14
	s_mov_b64 s[8:9], 0x1000
	v_lshl_add_u64 v[2:3], v[0:1], 0, s[8:9]
	s_mov_b64 s[8:9], 0x1100
	s_waitcnt lgkmcnt(0)
	v_lshl_add_u64 v[4:5], v[0:1], 0, s[8:9]
	s_lshr_b32 s12, s10, 16
	s_and_b32 s10, s10, 0xffff
	s_cmp_lg_u32 s10, 0
	s_cselect_b64 s[10:11], -1, 0
	s_cmp_lg_u64 s[10:11], 0
	s_addc_u32 s10, s87, 0
	s_cmp_lg_u32 s12, 0
	s_mul_i32 s28, s10, s68
	s_cselect_b64 s[10:11], -1, 0
	s_cmp_lg_u64 s[10:11], 0
	s_load_dword s10, s[0:1], 0xe8
	s_mov_b64 s[8:9], 0x1200
	v_lshl_add_u64 v[6:7], v[0:1], 0, s[8:9]
	s_mov_b64 s[8:9], 0x1300
	v_lshl_add_u64 v[8:9], v[0:1], 0, s[8:9]
	s_waitcnt lgkmcnt(0)
	s_addc_u32 s10, s10, 0
	s_mul_i32 s28, s28, s10
	s_mov_b32 s29, 1
	s_mov_b64 s[8:9], 0
	s_branch .LBB0_634

.LBB0_752:
	s_mov_b64 s[8:9], s[0:1]
	s_waitcnt vmcnt(0) lgkmcnt(0)
	v_mov_b64_e32 v[0:1], s[8:9]
	flat_load_dwordx2 v[0:1], v[0:1] offset:216
	s_getreg_b32 s3, hwreg(HW_REG_XCC_ID, 0, 4)
	s_waitcnt vmcnt(0)
	s_waitcnt lgkmcnt(0)
	s_barrier
	v_readlane_b32 s98, v254, 2
	v_readfirstlane_b32 s100, v176
	s_nop 0
	s_lshr_b32 s100, s100, 6
	s_cmp_eq_u32 s100, 1
	s_cselect_b32 s100, s98, 0
	s_cmp_lg_u32 s100, 0
	s_cbranch_scc0 .Lew_7
	buffer_inv sc1
	s_waitcnt vmcnt(0)

.Lew_10:
	s_and_saveexec_b64 s[48:49], s[24:25]
	s_cbranch_execz .LBB0_1049
	s_add_i32 s8, 0, 0x23ff0
	v_mov_b32_e32 v2, s8
	s_waitcnt vmcnt(0) expcnt(0) lgkmcnt(0)
	ds_read_b32 v6, v2
	s_add_i32 s8, 0, 0x23ff4
	v_mov_b32_e32 v2, s8
	ds_read_b32 v4, v2
	s_and_b32 s3, s3, 15
	s_waitcnt lgkmcnt(1)
	v_cmp_ne_u32_e32 vcc, 0, v6
	s_cbranch_vccnz .LBB0_1020
	v_readlane_b32 s8, v254, 0
	v_readlane_b32 s9, v254, 1
	s_load_dword s10, s[8:9], 0x14
	s_mov_b64 s[8:9], 0x1000
	v_lshl_add_u64 v[2:3], v[0:1], 0, s[8:9]
	s_mov_b64 s[8:9], 0x1100
	s_waitcnt lgkmcnt(0)
	v_lshl_add_u64 v[4:5], v[0:1], 0, s[8:9]
	s_lshr_b32 s12, s10, 16
	s_and_b32 s10, s10, 0xffff
	s_cmp_lg_u32 s10, 0
	s_cselect_b64 s[10:11], -1, 0
	s_cmp_lg_u64 s[10:11], 0
	s_addc_u32 s10, s87, 0
	s_cmp_lg_u32 s12, 0
	s_mul_i32 s28, s10, s68
	s_cselect_b64 s[10:11], -1, 0
	s_cmp_lg_u64 s[10:11], 0
	s_load_dword s10, s[0:1], 0xe8
	s_mov_b64 s[8:9], 0x1200
	v_lshl_add_u64 v[6:7], v[0:1], 0, s[8:9]
	s_mov_b64 s[8:9], 0x1300
	v_lshl_add_u64 v[8:9], v[0:1], 0, s[8:9]
	s_waitcnt lgkmcnt(0)
	s_addc_u32 s10, s10, 0
	s_mul_i32 s28, s28, s10
	s_mov_b32 s29, 1
	s_mov_b64 s[8:9], 0
	s_branch .LBB0_1010

.LBB0_1071:
	v_writelane_b32 v255, s11, 0
	v_writelane_b32 v255, s12, 1
	v_writelane_b32 v255, s13, 2
	v_writelane_b32 v255, s14, 3
	v_writelane_b32 v255, s15, 4
	v_writelane_b32 v255, s16, 5
	v_writelane_b32 v255, s17, 6
	v_writelane_b32 v255, s21, 7
	v_writelane_b32 v255, s22, 8
	v_writelane_b32 v255, s23, 9
	v_writelane_b32 v255, s26, 10
	v_writelane_b32 v255, s28, 11
	v_writelane_b32 v255, s34, 12
	s_mov_b64 s[8:9], s[0:1]
	s_waitcnt lgkmcnt(0)
	s_barrier
	s_nop 0
	v_mov_b64_e32 v[0:1], s[8:9]
	flat_load_dwordx2 v[0:1], v[0:1] offset:216
	s_getreg_b32 s3, hwreg(HW_REG_XCC_ID, 0, 4)
	s_waitcnt vmcnt(0)
	s_waitcnt lgkmcnt(0)
	s_barrier
	v_readlane_b32 s98, v254, 2
	v_readfirstlane_b32 s100, v176
	s_nop 0
	s_lshr_b32 s100, s100, 6
	s_cmp_eq_u32 s100, 1
	s_cselect_b32 s100, s98, 0
	s_cmp_lg_u32 s100, 0
	s_cbranch_scc0 .Lb21_ew_11
	buffer_inv sc1
	s_waitcnt vmcnt(0)

.LBB0_1104:
	s_mov_b64 s[8:9], s[0:1]
	s_waitcnt lgkmcnt(0)
	s_barrier
	s_nop 0
	v_mov_b64_e32 v[0:1], s[8:9]
	flat_load_dwordx2 v[0:1], v[0:1] offset:216
	s_getreg_b32 s3, hwreg(HW_REG_XCC_ID, 0, 4)
	s_waitcnt vmcnt(0)
	s_waitcnt lgkmcnt(0)
	s_barrier
	v_readlane_b32 s98, v254, 2
	v_readfirstlane_b32 s100, v176
	s_nop 0
	s_lshr_b32 s100, s100, 6
	s_cmp_eq_u32 s100, 1
	s_cselect_b32 s100, s98, 0
	s_cmp_lg_u32 s100, 0
	s_cbranch_scc0 .Lew_11
	buffer_inv sc1
	s_waitcnt vmcnt(0)

.LBB0_1182:
	s_mov_b64 s[8:9], s[0:1]
	s_nop 0
	v_mov_b64_e32 v[0:1], s[8:9]
	flat_load_dwordx2 v[0:1], v[0:1] offset:216
	s_getreg_b32 s3, hwreg(HW_REG_XCC_ID, 0, 4)
	s_waitcnt vmcnt(0)
	s_waitcnt lgkmcnt(0)
	s_barrier
	v_readlane_b32 s98, v254, 2
	v_readfirstlane_b32 s100, v176
	s_nop 0
	s_lshr_b32 s100, s100, 6
	s_cmp_eq_u32 s100, 1
	s_cselect_b32 s100, s98, 0
	s_cmp_lg_u32 s100, 0
	s_cbranch_scc0 .Lew_12
	buffer_inv sc1
	s_waitcnt vmcnt(0)

.Lew_14:
	s_and_saveexec_b64 s[38:39], s[24:25]
	s_cbranch_execz .LBB0_1410
	s_add_i32 s6, 0, 0x23ff0
	v_mov_b32_e32 v2, s6
	s_waitcnt vmcnt(0) expcnt(0) lgkmcnt(0)
	ds_read_b32 v6, v2
	s_add_i32 s6, 0, 0x23ff4
	v_mov_b32_e32 v2, s6
	ds_read_b32 v4, v2
	s_and_b32 s3, s3, 15
	s_waitcnt lgkmcnt(1)
	v_cmp_ne_u32_e32 vcc, 0, v6
	s_cbranch_vccnz .LBB0_1381
	v_readlane_b32 s6, v254, 0
	v_readlane_b32 s7, v254, 1
	s_load_dword s8, s[6:7], 0x14
	s_mov_b64 s[6:7], 0x1000
	v_lshl_add_u64 v[2:3], v[0:1], 0, s[6:7]
	s_mov_b64 s[6:7], 0x1100
	s_waitcnt lgkmcnt(0)
	v_lshl_add_u64 v[4:5], v[0:1], 0, s[6:7]
	s_lshr_b32 s10, s8, 16
	s_and_b32 s8, s8, 0xffff
	s_cmp_lg_u32 s8, 0
	s_cselect_b64 s[8:9], -1, 0
	s_cmp_lg_u64 s[8:9], 0
	s_addc_u32 s8, s87, 0
	s_cmp_lg_u32 s10, 0
	s_mul_i32 s24, s8, s68
	s_cselect_b64 s[8:9], -1, 0
	s_cmp_lg_u64 s[8:9], 0
	s_load_dword s8, s[0:1], 0xe8
	s_mov_b64 s[6:7], 0x1200
	v_lshl_add_u64 v[6:7], v[0:1], 0, s[6:7]
	s_mov_b64 s[6:7], 0x1300
	v_lshl_add_u64 v[8:9], v[0:1], 0, s[6:7]
	s_waitcnt lgkmcnt(0)
	s_addc_u32 s8, s8, 0
	s_mul_i32 s24, s24, s8
	s_mov_b32 s25, 1
	s_mov_b64 s[6:7], 0
	s_branch .LBB0_1371
